# plus batched f32-residual loads in P2 epilogue (4-group rolling window)
# baseline (speedup 1.0000x reference)
;     __device__ __forceinline__ void operator()(AccRef acc, const Unit& u, int wr, int wc, int fr, int fq) const {
;     ...
; #pragma unroll
;         for (int ai = 0; ai < 2; ++ai)
; #pragma unroll
;             for (int m = 0; m < 4; ++m) {
;                 const int row = row0 + ai * HALF + m * 16;
;                 const size_t off = (size_t)row * D + col0;
;                 if constexpr (LNRES) {
;                     const f32x2v st = *(const f32x2v*)(stats + 2 * (size_t)row);
;                     const float mean = st.x, rstd = st.y;
; #pragma unroll
;                     for (int bj = 0; bj < 2; ++bj) {
;                         const f32x4 z0 = *(const f32x4*)(res + off + bj * HALF), z1 = *(const f32x4*)(res + off + bj * HALF + 4);
;                         *(f32x4*)(out + off + bj * HALF) = (z0 - mean) * rstd * ga[bj][0] + ba[bj][0] + acc[ai][bj][m][0] * s;
;                         *(f32x4*)(out + off + bj * HALF + 4) = (z1 - mean) * rstd * ga[bj][1] + ba[bj][1] + acc[ai][bj][m][1] * s;
;                     }
;                 } else {
; #pragma unroll
;                     for (int bj = 0; bj < 2; ++bj) {
;                         const f32x4 r0 = *(const f32x4*)(res + off + bj * HALF), r1 = *(const f32x4*)(res + off + bj * HALF + 4);
;                         *(f32x4*)(out + off + bj * HALF) = r0 * alpha + acc[ai][bj][m][0] * s;
;                         *(f32x4*)(out + off + bj * HALF + 4) = r1 * alpha + acc[ai][bj][m][1] * s;
;                     }
;                 }
;                 if (m & 1) asm volatile("" ::: "memory");
;             }
.LBB0_225:
	v_mov_b32_e32 v145, v147
	v_mov_b32_e32 v144, v146
	s_lshl_b32 s34, s65, 8
	s_add_i32 s34, s34, s54
	v_add_u32_e32 v144, s34, v144
	s_lshl_b32 s34, s66, 8
	s_or_b32 s34, s34, s55
	v_lshl_add_u32 v152, v145, 3, s34
	v_ashrrev_i32_e32 v145, 31, v144
	v_ashrrev_i32_e32 v153, 31, v152
	v_lshlrev_b64 v[144:145], 11, v[144:145]
	v_lshl_add_u64 v[144:145], v[144:145], 0, v[152:153]
	v_lshlrev_b64 v[144:145], 2, v[144:145]
	s_and_b64 vcc, exec, s[0:1]
	s_mov_b64 s[0:1], -1
	v_lshl_add_u64 v[238:239], s[2:3], 0, v[144:145]
	global_load_dwordx4 v[160:163], v[238:239], off
	global_load_dwordx4 v[164:167], v[238:239], off offset:16
	global_load_dwordx4 v[168:171], v[238:239], off offset:512
	global_load_dwordx4 v[172:175], v[238:239], off offset:528
	v_lshl_add_u64 v[224:225], v[144:145], 0, s[18:19]
	v_lshl_add_u64 v[240:241], s[2:3], 0, v[224:225]
	global_load_dwordx4 v[176:179], v[240:241], off
	global_load_dwordx4 v[180:183], v[240:241], off offset:16
	global_load_dwordx4 v[184:187], v[240:241], off offset:512
	global_load_dwordx4 v[188:191], v[240:241], off offset:528
	v_lshl_add_u64 v[226:227], v[144:145], 0, s[20:21]
	v_lshl_add_u64 v[242:243], s[2:3], 0, v[226:227]
	global_load_dwordx4 v[192:195], v[242:243], off
	global_load_dwordx4 v[196:199], v[242:243], off offset:16
	global_load_dwordx4 v[200:203], v[242:243], off offset:512
	global_load_dwordx4 v[204:207], v[242:243], off offset:528
	v_lshl_add_u64 v[228:229], v[144:145], 0, s[22:23]
	v_lshl_add_u64 v[244:245], s[2:3], 0, v[228:229]
	global_load_dwordx4 v[208:211], v[244:245], off
	global_load_dwordx4 v[212:215], v[244:245], off offset:16
	global_load_dwordx4 v[216:219], v[244:245], off offset:512
	global_load_dwordx4 v[220:223], v[244:245], off offset:528
	v_lshl_add_u64 v[152:153], s[6:7], 0, v[144:145]
	s_waitcnt vmcnt(12)
	v_pk_mul_f32 v[162:163], v[162:163], s[16:17] op_sel_hi:[1,0]
	v_pk_mul_f32 v[160:161], v[160:161], s[16:17] op_sel_hi:[1,0]
	v_pk_mul_f32 v[166:167], v[166:167], s[16:17] op_sel_hi:[1,0]
	v_pk_mul_f32 v[164:165], v[164:165], s[16:17] op_sel_hi:[1,0]
	v_pk_mul_f32 v[170:171], v[170:171], s[16:17] op_sel_hi:[1,0]
	v_pk_mul_f32 v[168:169], v[168:169], s[16:17] op_sel_hi:[1,0]
	v_pk_mul_f32 v[174:175], v[174:175], s[16:17] op_sel_hi:[1,0]
	v_pk_mul_f32 v[172:173], v[172:173], s[16:17] op_sel_hi:[1,0]
	v_pk_fma_f32 v[126:127], v[126:127], 0.5, v[162:163] op_sel_hi:[1,0,1]
	v_pk_fma_f32 v[124:125], v[124:125], 0.5, v[160:161] op_sel_hi:[1,0,1]
	v_pk_fma_f32 v[122:123], v[122:123], 0.5, v[166:167] op_sel_hi:[1,0,1]
	v_pk_fma_f32 v[120:121], v[120:121], 0.5, v[164:165] op_sel_hi:[1,0,1]
	v_pk_fma_f32 v[118:119], v[118:119], 0.5, v[170:171] op_sel_hi:[1,0,1]
	v_pk_fma_f32 v[116:117], v[116:117], 0.5, v[168:169] op_sel_hi:[1,0,1]
	v_pk_fma_f32 v[110:111], v[110:111], 0.5, v[174:175] op_sel_hi:[1,0,1]
	v_pk_fma_f32 v[108:109], v[108:109], 0.5, v[172:173] op_sel_hi:[1,0,1]
	global_store_dwordx4 v[152:153], v[124:127], off
	global_store_dwordx4 v[152:153], v[120:123], off offset:16
	global_store_dwordx4 v[152:153], v[116:119], off offset:512
	global_store_dwordx4 v[152:153], v[108:111], off offset:528
	v_lshl_add_u64 v[230:231], v[144:145], 0, s[24:25]
	v_lshl_add_u64 v[246:247], s[2:3], 0, v[230:231]
	global_load_dwordx4 v[160:163], v[246:247], off
	global_load_dwordx4 v[164:167], v[246:247], off offset:16
	global_load_dwordx4 v[168:171], v[246:247], off offset:512
	global_load_dwordx4 v[172:175], v[246:247], off offset:528
	v_lshl_add_u64 v[154:155], s[6:7], 0, v[224:225]
	s_waitcnt vmcnt(16)
	v_pk_mul_f32 v[178:179], v[178:179], s[16:17] op_sel_hi:[1,0]
	v_pk_mul_f32 v[176:177], v[176:177], s[16:17] op_sel_hi:[1,0]
	v_pk_mul_f32 v[182:183], v[182:183], s[16:17] op_sel_hi:[1,0]
	v_pk_mul_f32 v[180:181], v[180:181], s[16:17] op_sel_hi:[1,0]
	v_pk_mul_f32 v[186:187], v[186:187], s[16:17] op_sel_hi:[1,0]
	v_pk_mul_f32 v[184:185], v[184:185], s[16:17] op_sel_hi:[1,0]
	v_pk_mul_f32 v[190:191], v[190:191], s[16:17] op_sel_hi:[1,0]
	v_pk_mul_f32 v[188:189], v[188:189], s[16:17] op_sel_hi:[1,0]
	v_pk_fma_f32 v[114:115], v[114:115], 0.5, v[178:179] op_sel_hi:[1,0,1]
	v_pk_fma_f32 v[112:113], v[112:113], 0.5, v[176:177] op_sel_hi:[1,0,1]
	v_pk_fma_f32 v[106:107], v[106:107], 0.5, v[182:183] op_sel_hi:[1,0,1]
	v_pk_fma_f32 v[104:105], v[104:105], 0.5, v[180:181] op_sel_hi:[1,0,1]
	v_pk_fma_f32 v[102:103], v[102:103], 0.5, v[186:187] op_sel_hi:[1,0,1]
	v_pk_fma_f32 v[100:101], v[100:101], 0.5, v[184:185] op_sel_hi:[1,0,1]
	v_pk_fma_f32 v[94:95], v[94:95], 0.5, v[190:191] op_sel_hi:[1,0,1]
	v_pk_fma_f32 v[92:93], v[92:93], 0.5, v[188:189] op_sel_hi:[1,0,1]
	global_store_dwordx4 v[154:155], v[112:115], off
	global_store_dwordx4 v[154:155], v[104:107], off offset:16
	global_store_dwordx4 v[154:155], v[100:103], off offset:512
	global_store_dwordx4 v[154:155], v[92:95], off offset:528
	v_lshl_add_u64 v[232:233], v[144:145], 0, s[26:27]
	v_lshl_add_u64 v[248:249], s[2:3], 0, v[232:233]
	global_load_dwordx4 v[176:179], v[248:249], off
	global_load_dwordx4 v[180:183], v[248:249], off offset:16
	global_load_dwordx4 v[184:187], v[248:249], off offset:512
	global_load_dwordx4 v[188:191], v[248:249], off offset:528
	v_lshl_add_u64 v[152:153], s[6:7], 0, v[226:227]
	s_waitcnt vmcnt(20)
;     __device__ __forceinline__ void operator()(AccRef acc, const Unit& u, int wr, int wc, int fr, int fq) const {
;     ...
; #pragma unroll
;         for (int ai = 0; ai < 2; ++ai)
; #pragma unroll
;             for (int m = 0; m < 4; ++m) {
;                 const int row = row0 + ai * HALF + m * 16;
;                 const size_t off = (size_t)row * D + col0;
;                 if constexpr (LNRES) {
;                     const f32x2v st = *(const f32x2v*)(stats + 2 * (size_t)row);
;                     const float mean = st.x, rstd = st.y;
; #pragma unroll
;                     for (int bj = 0; bj < 2; ++bj) {
;                         const f32x4 z0 = *(const f32x4*)(res + off + bj * HALF), z1 = *(const f32x4*)(res + off + bj * HALF + 4);
;                         *(f32x4*)(out + off + bj * HALF) = (z0 - mean) * rstd * ga[bj][0] + ba[bj][0] + acc[ai][bj][m][0] * s;
;                         *(f32x4*)(out + off + bj * HALF + 4) = (z1 - mean) * rstd * ga[bj][1] + ba[bj][1] + acc[ai][bj][m][1] * s;
;                     }
;                 } else {
; #pragma unroll
;                     for (int bj = 0; bj < 2; ++bj) {
;                         const f32x4 r0 = *(const f32x4*)(res + off + bj * HALF), r1 = *(const f32x4*)(res + off + bj * HALF + 4);
;                         *(f32x4*)(out + off + bj * HALF) = r0 * alpha + acc[ai][bj][m][0] * s;
;                         *(f32x4*)(out + off + bj * HALF + 4) = r1 * alpha + acc[ai][bj][m][1] * s;
;                     }
;                 }
;                 if (m & 1) asm volatile("" ::: "memory");
;             }
	v_pk_mul_f32 v[194:195], v[194:195], s[16:17] op_sel_hi:[1,0]
	v_pk_mul_f32 v[192:193], v[192:193], s[16:17] op_sel_hi:[1,0]
	v_pk_mul_f32 v[198:199], v[198:199], s[16:17] op_sel_hi:[1,0]
	v_pk_mul_f32 v[196:197], v[196:197], s[16:17] op_sel_hi:[1,0]
	v_pk_mul_f32 v[202:203], v[202:203], s[16:17] op_sel_hi:[1,0]
	v_pk_mul_f32 v[200:201], v[200:201], s[16:17] op_sel_hi:[1,0]
	v_pk_mul_f32 v[206:207], v[206:207], s[16:17] op_sel_hi:[1,0]
	v_pk_mul_f32 v[204:205], v[204:205], s[16:17] op_sel_hi:[1,0]
	v_pk_fma_f32 v[98:99], v[98:99], 0.5, v[194:195] op_sel_hi:[1,0,1]
	v_pk_fma_f32 v[96:97], v[96:97], 0.5, v[192:193] op_sel_hi:[1,0,1]
	v_pk_fma_f32 v[90:91], v[90:91], 0.5, v[198:199] op_sel_hi:[1,0,1]
	v_pk_fma_f32 v[88:89], v[88:89], 0.5, v[196:197] op_sel_hi:[1,0,1]
	v_pk_fma_f32 v[86:87], v[86:87], 0.5, v[202:203] op_sel_hi:[1,0,1]
	v_pk_fma_f32 v[84:85], v[84:85], 0.5, v[200:201] op_sel_hi:[1,0,1]
	v_pk_fma_f32 v[78:79], v[78:79], 0.5, v[206:207] op_sel_hi:[1,0,1]
	v_pk_fma_f32 v[76:77], v[76:77], 0.5, v[204:205] op_sel_hi:[1,0,1]
	global_store_dwordx4 v[152:153], v[96:99], off
	global_store_dwordx4 v[152:153], v[88:91], off offset:16
	global_store_dwordx4 v[152:153], v[84:87], off offset:512
	global_store_dwordx4 v[152:153], v[76:79], off offset:528
	v_lshl_add_u64 v[234:235], v[144:145], 0, s[28:29]
	v_lshl_add_u64 v[250:251], s[2:3], 0, v[234:235]
	global_load_dwordx4 v[192:195], v[250:251], off
	global_load_dwordx4 v[196:199], v[250:251], off offset:16
	global_load_dwordx4 v[200:203], v[250:251], off offset:512
	global_load_dwordx4 v[204:207], v[250:251], off offset:528
	v_lshl_add_u64 v[154:155], s[6:7], 0, v[228:229]
	s_waitcnt vmcnt(24)
	v_pk_mul_f32 v[210:211], v[210:211], s[16:17] op_sel_hi:[1,0]
	v_pk_mul_f32 v[208:209], v[208:209], s[16:17] op_sel_hi:[1,0]
	v_pk_mul_f32 v[214:215], v[214:215], s[16:17] op_sel_hi:[1,0]
	v_pk_mul_f32 v[212:213], v[212:213], s[16:17] op_sel_hi:[1,0]
	v_pk_mul_f32 v[218:219], v[218:219], s[16:17] op_sel_hi:[1,0]
	v_pk_mul_f32 v[216:217], v[216:217], s[16:17] op_sel_hi:[1,0]
	v_pk_mul_f32 v[222:223], v[222:223], s[16:17] op_sel_hi:[1,0]
	v_pk_mul_f32 v[220:221], v[220:221], s[16:17] op_sel_hi:[1,0]
	v_pk_fma_f32 v[82:83], v[82:83], 0.5, v[210:211] op_sel_hi:[1,0,1]
	v_pk_fma_f32 v[80:81], v[80:81], 0.5, v[208:209] op_sel_hi:[1,0,1]
	v_pk_fma_f32 v[74:75], v[74:75], 0.5, v[214:215] op_sel_hi:[1,0,1]
	v_pk_fma_f32 v[72:73], v[72:73], 0.5, v[212:213] op_sel_hi:[1,0,1]
	v_pk_fma_f32 v[70:71], v[70:71], 0.5, v[218:219] op_sel_hi:[1,0,1]
	v_pk_fma_f32 v[68:69], v[68:69], 0.5, v[216:217] op_sel_hi:[1,0,1]
	v_pk_fma_f32 v[66:67], v[66:67], 0.5, v[222:223] op_sel_hi:[1,0,1]
	v_pk_fma_f32 v[64:65], v[64:65], 0.5, v[220:221] op_sel_hi:[1,0,1]
	global_store_dwordx4 v[154:155], v[80:83], off
	global_store_dwordx4 v[154:155], v[72:75], off offset:16
	global_store_dwordx4 v[154:155], v[68:71], off offset:512
	global_store_dwordx4 v[154:155], v[64:67], off offset:528
	v_lshl_add_u64 v[236:237], v[144:145], 0, s[8:9]
	v_lshl_add_u64 v[252:253], s[2:3], 0, v[236:237]
	global_load_dwordx4 v[208:211], v[252:253], off
	global_load_dwordx4 v[212:215], v[252:253], off offset:16
	global_load_dwordx4 v[216:219], v[252:253], off offset:512
	global_load_dwordx4 v[220:223], v[252:253], off offset:528
	v_lshl_add_u64 v[152:153], s[6:7], 0, v[230:231]
	s_waitcnt vmcnt(24)
	v_pk_mul_f32 v[162:163], v[162:163], s[16:17] op_sel_hi:[1,0]
	v_pk_mul_f32 v[160:161], v[160:161], s[16:17] op_sel_hi:[1,0]
	v_pk_mul_f32 v[166:167], v[166:167], s[16:17] op_sel_hi:[1,0]
	v_pk_mul_f32 v[164:165], v[164:165], s[16:17] op_sel_hi:[1,0]
	v_pk_mul_f32 v[170:171], v[170:171], s[16:17] op_sel_hi:[1,0]
	v_pk_mul_f32 v[168:169], v[168:169], s[16:17] op_sel_hi:[1,0]
	v_pk_mul_f32 v[174:175], v[174:175], s[16:17] op_sel_hi:[1,0]
	v_pk_mul_f32 v[172:173], v[172:173], s[16:17] op_sel_hi:[1,0]
	v_pk_fma_f32 v[62:63], v[62:63], 0.5, v[162:163] op_sel_hi:[1,0,1]
	v_pk_fma_f32 v[60:61], v[60:61], 0.5, v[160:161] op_sel_hi:[1,0,1]
	v_pk_fma_f32 v[58:59], v[58:59], 0.5, v[166:167] op_sel_hi:[1,0,1]
	v_pk_fma_f32 v[56:57], v[56:57], 0.5, v[164:165] op_sel_hi:[1,0,1]
	v_pk_fma_f32 v[54:55], v[54:55], 0.5, v[170:171] op_sel_hi:[1,0,1]
	v_pk_fma_f32 v[52:53], v[52:53], 0.5, v[168:169] op_sel_hi:[1,0,1]
	v_pk_fma_f32 v[46:47], v[46:47], 0.5, v[174:175] op_sel_hi:[1,0,1]
	v_pk_fma_f32 v[44:45], v[44:45], 0.5, v[172:173] op_sel_hi:[1,0,1]
	global_store_dwordx4 v[152:153], v[60:63], off
	global_store_dwordx4 v[152:153], v[56:59], off offset:16
	global_store_dwordx4 v[152:153], v[52:55], off offset:512
	global_store_dwordx4 v[152:153], v[44:47], off offset:528
	v_lshl_add_u64 v[154:155], s[6:7], 0, v[232:233]
	s_waitcnt vmcnt(20)
; #define PG8_BAR __builtin_amdgcn_s_barrier()
; template <class Epi>
; __device__ __forceinline__ void gemm_phase(ldsp lds, const Gemm g, const StaticOrder& S, const Epi& E, int wave0) {
;     ...
;         if (!has_next) break;
; #pragma unroll
;         for (int a = 0; a < 2; ++a)
; #pragma unroll
;             for (int b = 0; b < 2; ++b)
; #pragma unroll
;                 for (int m = 0; m < 4; ++m)
; #pragma unroll
;                     for (int n = 0; n < 2; ++n) acc[a][b][m][n] = (f32x4){0.f, 0.f, 0.f, 0.f};
;         cur = nxt; cA = nA; cB = nB; ++ui;
;         if (wr == 1) PG8_BAR;
;     __device__ __forceinline__ void operator()(AccRef acc, const Unit& u, int wr, int wc, int fr, int fq) const {
;     ...
; #pragma unroll
;         for (int ai = 0; ai < 2; ++ai)
; #pragma unroll
;             for (int m = 0; m < 4; ++m) {
;                 const int row = row0 + ai * HALF + m * 16;
;                 const size_t off = (size_t)row * D + col0;
;                 if constexpr (LNRES) {
;                     const f32x2v st = *(const f32x2v*)(stats + 2 * (size_t)row);
;                     const float mean = st.x, rstd = st.y;
; #pragma unroll
;                     for (int bj = 0; bj < 2; ++bj) {
;                         const f32x4 z0 = *(const f32x4*)(res + off + bj * HALF), z1 = *(const f32x4*)(res + off + bj * HALF + 4);
;                         *(f32x4*)(out + off + bj * HALF) = (z0 - mean) * rstd * ga[bj][0] + ba[bj][0] + acc[ai][bj][m][0] * s;
;                         *(f32x4*)(out + off + bj * HALF + 4) = (z1 - mean) * rstd * ga[bj][1] + ba[bj][1] + acc[ai][bj][m][1] * s;
;                     }
;                 } else {
; #pragma unroll
;                     for (int bj = 0; bj < 2; ++bj) {
;                         const f32x4 r0 = *(const f32x4*)(res + off + bj * HALF), r1 = *(const f32x4*)(res + off + bj * HALF + 4);
;                         *(f32x4*)(out + off + bj * HALF) = r0 * alpha + acc[ai][bj][m][0] * s;
;                         *(f32x4*)(out + off + bj * HALF + 4) = r1 * alpha + acc[ai][bj][m][1] * s;
;                     }
;                 }
;                 if (m & 1) asm volatile("" ::: "memory");
;             }
	v_pk_mul_f32 v[178:179], v[178:179], s[16:17] op_sel_hi:[1,0]
	v_pk_mul_f32 v[176:177], v[176:177], s[16:17] op_sel_hi:[1,0]
	v_pk_mul_f32 v[182:183], v[182:183], s[16:17] op_sel_hi:[1,0]
	v_pk_mul_f32 v[180:181], v[180:181], s[16:17] op_sel_hi:[1,0]
	v_pk_mul_f32 v[186:187], v[186:187], s[16:17] op_sel_hi:[1,0]
	v_pk_mul_f32 v[184:185], v[184:185], s[16:17] op_sel_hi:[1,0]
	v_pk_mul_f32 v[190:191], v[190:191], s[16:17] op_sel_hi:[1,0]
	v_pk_mul_f32 v[188:189], v[188:189], s[16:17] op_sel_hi:[1,0]
	v_pk_fma_f32 v[50:51], v[50:51], 0.5, v[178:179] op_sel_hi:[1,0,1]
	v_pk_fma_f32 v[48:49], v[48:49], 0.5, v[176:177] op_sel_hi:[1,0,1]
	v_pk_fma_f32 v[42:43], v[42:43], 0.5, v[182:183] op_sel_hi:[1,0,1]
	v_pk_fma_f32 v[40:41], v[40:41], 0.5, v[180:181] op_sel_hi:[1,0,1]
	v_pk_fma_f32 v[38:39], v[38:39], 0.5, v[186:187] op_sel_hi:[1,0,1]
	v_pk_fma_f32 v[36:37], v[36:37], 0.5, v[184:185] op_sel_hi:[1,0,1]
	v_pk_fma_f32 v[30:31], v[30:31], 0.5, v[190:191] op_sel_hi:[1,0,1]
	v_pk_fma_f32 v[28:29], v[28:29], 0.5, v[188:189] op_sel_hi:[1,0,1]
	global_store_dwordx4 v[154:155], v[48:51], off
	global_store_dwordx4 v[154:155], v[40:43], off offset:16
	global_store_dwordx4 v[154:155], v[36:39], off offset:512
	global_store_dwordx4 v[154:155], v[28:31], off offset:528
	v_lshl_add_u64 v[152:153], s[6:7], 0, v[234:235]
	s_waitcnt vmcnt(16)
	v_pk_mul_f32 v[194:195], v[194:195], s[16:17] op_sel_hi:[1,0]
	v_pk_mul_f32 v[192:193], v[192:193], s[16:17] op_sel_hi:[1,0]
	v_pk_mul_f32 v[198:199], v[198:199], s[16:17] op_sel_hi:[1,0]
	v_pk_mul_f32 v[196:197], v[196:197], s[16:17] op_sel_hi:[1,0]
	v_pk_mul_f32 v[202:203], v[202:203], s[16:17] op_sel_hi:[1,0]
	v_pk_mul_f32 v[200:201], v[200:201], s[16:17] op_sel_hi:[1,0]
	v_pk_mul_f32 v[206:207], v[206:207], s[16:17] op_sel_hi:[1,0]
	v_pk_mul_f32 v[204:205], v[204:205], s[16:17] op_sel_hi:[1,0]
	v_pk_fma_f32 v[34:35], v[34:35], 0.5, v[194:195] op_sel_hi:[1,0,1]
	v_pk_fma_f32 v[32:33], v[32:33], 0.5, v[192:193] op_sel_hi:[1,0,1]
	v_pk_fma_f32 v[26:27], v[26:27], 0.5, v[198:199] op_sel_hi:[1,0,1]
	v_pk_fma_f32 v[24:25], v[24:25], 0.5, v[196:197] op_sel_hi:[1,0,1]
	v_pk_fma_f32 v[22:23], v[22:23], 0.5, v[202:203] op_sel_hi:[1,0,1]
	v_pk_fma_f32 v[20:21], v[20:21], 0.5, v[200:201] op_sel_hi:[1,0,1]
	v_pk_fma_f32 v[14:15], v[14:15], 0.5, v[206:207] op_sel_hi:[1,0,1]
	v_pk_fma_f32 v[12:13], v[12:13], 0.5, v[204:205] op_sel_hi:[1,0,1]
	global_store_dwordx4 v[152:153], v[32:35], off
	global_store_dwordx4 v[152:153], v[24:27], off offset:16
	global_store_dwordx4 v[152:153], v[20:23], off offset:512
	global_store_dwordx4 v[152:153], v[12:15], off offset:528
	v_lshl_add_u64 v[154:155], s[6:7], 0, v[236:237]
	s_waitcnt vmcnt(12)
	v_pk_mul_f32 v[210:211], v[210:211], s[16:17] op_sel_hi:[1,0]
	v_pk_mul_f32 v[208:209], v[208:209], s[16:17] op_sel_hi:[1,0]
	v_pk_mul_f32 v[214:215], v[214:215], s[16:17] op_sel_hi:[1,0]
	v_pk_mul_f32 v[212:213], v[212:213], s[16:17] op_sel_hi:[1,0]
	v_pk_mul_f32 v[218:219], v[218:219], s[16:17] op_sel_hi:[1,0]
	v_pk_mul_f32 v[216:217], v[216:217], s[16:17] op_sel_hi:[1,0]
	v_pk_mul_f32 v[222:223], v[222:223], s[16:17] op_sel_hi:[1,0]
	v_pk_mul_f32 v[220:221], v[220:221], s[16:17] op_sel_hi:[1,0]
	v_pk_fma_f32 v[18:19], v[18:19], 0.5, v[210:211] op_sel_hi:[1,0,1]
	v_pk_fma_f32 v[16:17], v[16:17], 0.5, v[208:209] op_sel_hi:[1,0,1]
	v_pk_fma_f32 v[10:11], v[10:11], 0.5, v[214:215] op_sel_hi:[1,0,1]
	v_pk_fma_f32 v[8:9], v[8:9], 0.5, v[212:213] op_sel_hi:[1,0,1]
	v_pk_fma_f32 v[6:7], v[6:7], 0.5, v[218:219] op_sel_hi:[1,0,1]
	v_pk_fma_f32 v[4:5], v[4:5], 0.5, v[216:217] op_sel_hi:[1,0,1]
	v_pk_fma_f32 v[2:3], v[2:3], 0.5, v[222:223] op_sel_hi:[1,0,1]
	v_pk_fma_f32 v[0:1], v[0:1], 0.5, v[220:221] op_sel_hi:[1,0,1]
	global_store_dwordx4 v[154:155], v[16:19], off
	global_store_dwordx4 v[154:155], v[8:11], off offset:16
	global_store_dwordx4 v[154:155], v[4:7], off offset:512
	global_store_dwordx4 v[154:155], v[0:3], off offset:528
	s_cbranch_vccnz .LBB0_210
	s_andn2_b64 vcc, exec, s[10:11]
	s_cbranch_vccnz .LBB0_209
	s_barrier
	s_branch .LBB0_209
